# v36: v34 with the P1 start lag of the odd workgroups shortened from ~7.8 us to ~6.6 us
# speedup vs baseline: 1.0025x; 1.0025x over previous
; __device__ __forceinline__ int fresh_tid() { int t = threadIdx.x; asm volatile("" : "+v"(t)); return t; }
; __global__ void __launch_bounds__(NWAVES * 64, 2) fwd_megakernel(Args args) {
;     ...
;         pg8::Gemm g{R1, Win_t, DM, DM};
;         pg8::StaticOrder S; S.init(M, NIN, G, bx, 1);
;         pg8::EpiIn E{U, out, (const float*)(ws + WS_GT)};
;         pg8::gemm_phase<pg8::EpiIn, 0, 0, 16, 0, 0, 16>(lds, g, S, E, fresh_tid());
.LBB0_111:
	s_ashr_i32 s3, s93, 31
	v_writelane_b32 v254, s3, 9
	s_ashr_i32 s95, s94, 31
	s_bitcmp1_b32 s94, 0
	s_cbranch_scc0 .Lp1lag_skip
	s_sleep 127
	s_sleep 88
